# mlstm2: per-slice XM rows prefetched one chunk ahead (4 registers), drained at loop exit
# baseline (speedup 1.0000x reference)
; __device__ void mlstm2_phase(const Params& p, unsigned char* smem) {
;     ...
;     for (int unit = blockIdx.x; unit < 256; unit += gridDim.x) {
;     ...
;         }
;         __syncthreads();
;     }
.LBB0_414:
	s_waitcnt vmcnt(0)
	v_readlane_b32 s26, v251, 32
	v_readlane_b32 s27, v251, 33
	s_waitcnt lgkmcnt(0)
	s_barrier
	s_load_dword s26, s[26:27], 0x160
	v_readlane_b32 s28, v250, 43
	s_waitcnt lgkmcnt(0)
	s_add_i32 s28, s28, s26
	s_cmpk_gt_i32 s28, 0xff
	s_cbranch_scc1 .LBB0_527

; __device__ void mlstm2_phase(const Params& p, unsigned char* smem) {
;     ...
;         int sl = unit & 7, bh_ = unit >> 3;
;         if (gridDim.x == 256) { const int xcd_ = unit & 7, j_ = unit >> 3; bh_ = xcd_ * 4 + (j_ >> 3); sl = j_ & 7; }
;         const int h = bh_ & 7, b = bh_ >> 3;
;         f32x4 accC[3][2];
; #pragma unroll
;         for (int a = 0; a < 3; ++a)
; #pragma unroll
;             for (int c = 0; c < 2; ++c) accC[a][c] = (f32x4){0.f, 0.f, 0.f, 0.f};
;         for (int e = tid; e < 16 * 136; e += 512) { const int r = e / 136; Vt[32 * 136 + e] = (r == 0) ? (u16)0x3F80 : (u16)0; Vwt[32 * 136 + e] = 0; }
;         for (int e = tid; e < 48 * 264; e += 512) Ct[e] = 0;
;         if (tid == 0) gS[1] = 0.f;
;         const int vc = 256 * h + 32 * sl + 4 * (tid & 7);
;         const float* wvp = p.in[14] + (size_t)(vc >> 2) * 16;
;         __syncthreads();
;     ...
;             for (int i = 0; i < 2; ++i) { const int t = (tid + 512 * i) >> 3; const u32x2 raw = *(const u32x2*)(XM + (size_t)(row0 + t) * 2048 + vc);
.LBB0_418:
	v_add_u32_e32 v3, 0x200, v3
	s_movk_i32 s26, 0x2f7f
	v_cmp_lt_u32_e32 vcc, s26, v3
	ds_write_b16 v2, v93
	s_or_b64 s[52:53], vcc, s[52:53]
	v_add_u32_e32 v2, 0x400, v2
	s_andn2_b64 exec, exec, s[52:53]
	s_cbranch_execnz .LBB0_418
	s_or_b64 exec, exec, s[52:53]
	s_and_saveexec_b64 s[52:53], s[2:3]
	v_mov_b32_e32 v2, s33
	ds_write_b32 v2, v93
	s_or_b64 exec, exec, s[52:53]
	s_and_b32 s26, s28, 7
	s_ashr_i32 s27, s28, 3
	v_writelane_b32 v250, s28, 43
	s_ashr_i32 s52, s28, 6
	s_lshl_b32 s53, s26, 2
	v_readlane_b32 s28, v251, 45
	s_add_i32 s54, s53, s52
	v_readlane_b32 s29, v251, 46
	s_and_b64 s[52:53], s[28:29], exec
	s_cselect_b32 s54, s54, s27
	s_and_b32 s55, s54, 7
	s_and_b32 s27, s27, 7
	s_and_b64 s[52:53], s[28:29], exec
	s_cselect_b32 s26, s27, s26
	v_lshl_or_b32 v2, s26, 5, v110
	v_lshl_or_b32 v2, s55, 8, v2
	v_lshlrev_b32_e32 v92, 4, v2
	v_readlane_b32 s28, v251, 43
	v_readlane_b32 s52, v251, 32
	v_lshl_add_u64 v[100:101], s[80:81], 0, v[92:93]
	s_lshl_b32 s30, s55, 9
	v_lshlrev_b32_e32 v92, 1, v2
	v_readlane_b32 s29, v251, 44
	v_readlane_b32 s53, v251, 33
	v_lshl_add_u64 v[102:103], v[94:95], 0, s[30:31]
	v_lshl_add_u64 v[104:105], v[96:97], 0, s[30:31]
	v_lshl_add_u64 v[106:107], s[28:29], 0, v[92:93]
	s_mov_b64 s[56:57], s[30:31]
	s_load_dwordx4 s[28:31], s[52:53], 0x150
	s_lshl_b32 s27, s54, 9
	s_and_b32 s27, s27, 0xfffff000
	s_waitcnt lgkmcnt(0)
	s_mul_i32 s98, s54, 0xc000
	s_add_u32 s98, s28, s98
	s_addc_u32 s99, s29, 0
	s_add_u32 s98, s98, 0x1fa00000
	s_addc_u32 s99, s99, 0
	s_mov_b64 s[30:31], s[56:57]
	v_mov_b32_e32 v2, 0
	s_add_u32 s52, s28, s30
	s_addc_u32 s53, s29, 0
	s_lshl_b32 s26, s26, 6
	s_add_u32 s52, s52, s26
	s_addc_u32 s53, s53, 0
	s_lshl_b32 s26, s55, 2
	v_readlane_b32 s28, v250, 35
	s_add_u32 s88, s28, s26
	v_readlane_b32 s26, v250, 36
	v_lshl_add_u64 v[108:109], v[90:91], 1, s[52:53]
	s_addc_u32 s89, s26, 0
	v_or_b32_e32 v92, s27, v112
	v_add_u32_e32 v230, s27, v122
	v_or_b32_e32 v231, s27, v131
	v_or_b32_e32 v232, s27, v130
	v_add_u32_e32 v233, s27, v111
	v_or_b32_e32 v234, s27, v129
	v_or_b32_e32 v235, s27, v125
	v_or_b32_e32 v236, s27, v128
	v_or_b32_e32 v237, s27, v127
	v_or_b32_e32 v238, s27, v126
	s_mov_b32 s79, 0
	v_mov_b32_e32 v3, v2
	v_mov_b32_e32 v4, v2
	v_mov_b32_e32 v5, v2
	v_mov_b32_e32 v6, v2
	v_mov_b32_e32 v7, v2
	v_mov_b32_e32 v8, v2
	v_mov_b32_e32 v9, v2
	v_mov_b32_e32 v10, v2
	v_mov_b32_e32 v11, v2
	v_mov_b32_e32 v12, v2
	v_mov_b32_e32 v13, v2
	v_mov_b32_e32 v14, v2
	v_mov_b32_e32 v15, v2
	v_mov_b32_e32 v16, v2
	v_mov_b32_e32 v17, v2
	v_mov_b32_e32 v18, v2
	v_mov_b32_e32 v19, v2
	v_mov_b32_e32 v20, v2
	v_mov_b32_e32 v21, v2
	v_mov_b32_e32 v22, v2
	v_mov_b32_e32 v23, v2
	v_mov_b32_e32 v24, v2
	v_mov_b32_e32 v25, v2
	s_barrier
	v_add_u32_e32 v88, s79, v232
	v_ashrrev_i32_e32 v89, 31, v88
	v_lshlrev_b64 v[88:89], 12, v[88:89]
	v_lshl_add_u64 v[88:89], v[106:107], 0, v[88:89]
	global_load_dwordx2 v[224:225], v[88:89], off
	v_add_u32_e32 v88, s79, v231
	v_ashrrev_i32_e32 v89, 31, v88
	v_lshlrev_b64 v[88:89], 12, v[88:89]
	v_lshl_add_u64 v[88:89], v[106:107], 0, v[88:89]
	global_load_dword v218, v[88:89], off
	global_load_dword v228, v[88:89], off offset:4
	s_branch .LBB0_423

; __device__ void mlstm2_phase(const Params& p, unsigned char* smem) {
;     ...
;         for (int chunk = 0; chunk < 32; ++chunk) {
;             const int row0 = b * SEQL + chunk * 128, cu = bh_ * 32 + chunk;
; #pragma unroll
;             for (int i = 0; i < 8; ++i) { const int idx = tid + 512 * i, r = idx >> 5, cc = (idx & 31) * 8;
;                 *(u32x4*)(Ks + r * 264 + cc) = *(const u32x4*)(KX + (size_t)(row0 + r) * 2048 + 256 * h + cc); }
;             bf16x8 qf[8];
; #pragma unroll
;             for (int ks = 0; ks < 8; ++ks) qf[ks] = *(const bf16x8*)(Q + (size_t)(row0 + 16 * wave + l15) * 2048 + 256 * h + 32 * ks + 8 * lq);
;             float vv[2][4];
; #pragma unroll
;             for (int i = 0; i < 2; ++i) { const int t = (tid + 512 * i) >> 3; const u32x2 raw = *(const u32x2*)(XM + (size_t)(row0 + t) * 2048 + vc);
;                 const float x0 = bflo(raw.x), x1 = bfhi(raw.x), x2 = bflo(raw.y), x3 = bfhi(raw.y);
; #pragma unroll
;                 for (int jj = 0; jj < 4; ++jj) vv[i][jj] = x0 * wvp[jj] + x1 * wvp[4 + jj] + x2 * wvp[8 + jj] + x3 * wvp[12 + jj]; }
;             float m_new = 0.f;
;             const float* G = (const float*)(p.ws + OFF_G);
;             if (wave == 0) {
;                 const float m_prev = gS[1];
;                 const int t0 = 2 * lane;
;                 const float ig0 = G[(size_t)(row0 + t0) * 16 + h], fg0 = G[(size_t)(row0 + t0) * 16 + 8 + h];
;                 const float ig1 = G[(size_t)(row0 + t0 + 1) * 16 + h], fg1 = G[(size_t)(row0 + t0 + 1) * 16 + 8 + h];
;                 const float lf0 = -softplusf_(-fg0), lf1 = -softplusf_(-fg1);
;                 float s_ = lf0 + lf1;
; #pragma unroll
;                 for (int d = 1; d < 64; d <<= 1) { const float o = __shfl_up(s_, d); if (lane >= d) s_ += o; }
;                 const float b1 = s_, b0 = s_ - lf1;
;                 const float c0 = ig0 - b0, c1 = ig1 - b1;
;                 float mx = fmaxf(c0, c1);
; #pragma unroll
;                 for (int d = 1; d < 64; d <<= 1) { const float o = __shfl_up(mx, d); if (lane >= d) mx = fmaxf(mx, o); }
;                 float pm = __shfl_up(mx, 1); if (lane == 0) pm = -3.0e38f;
;                 const float M0p = fmaxf(pm, c0), M1p = mx;
;                 const float M0 = fmaxf(M0p, m_prev), M1 = fmaxf(M1p, m_prev);
;                 const float Ml = __shfl(M1, 63), bL = __shfl(b1, 63);
.LBB0_423:
	s_mul_i32 s30, s79, 12
	v_lshl_add_u32 v88, v112, 2, s30
	global_load_dwordx2 v[82:83], v88, s[98:99]
	global_load_dwordx2 v[84:85], v88, s[98:99] offset:512
	global_load_dwordx2 v[86:87], v88, s[98:99] offset:1024
	v_add_u32_e32 v30, s79, v235
	v_ashrrev_i32_e32 v31, 31, v30
	v_lshlrev_b64 v[26:27], 12, v[30:31]
	v_lshl_add_u64 v[26:27], v[102:103], 0, v[26:27]
	global_load_dwordx4 v[26:29], v[26:27], off
	v_add_u32_e32 v32, s79, v238
	v_ashrrev_i32_e32 v33, 31, v32
	v_lshlrev_b64 v[32:33], 12, v[32:33]
	v_lshl_add_u64 v[32:33], v[102:103], 0, v[32:33]
	global_load_dwordx4 v[32:35], v[32:33], off
	v_add_u32_e32 v36, 32, v30
	v_ashrrev_i32_e32 v37, 31, v36
	v_lshlrev_b64 v[36:37], 12, v[36:37]
	v_lshl_add_u64 v[36:37], v[102:103], 0, v[36:37]
	global_load_dwordx4 v[36:39], v[36:37], off
	v_add_u32_e32 v40, s79, v237
	v_ashrrev_i32_e32 v41, 31, v40
	v_lshlrev_b64 v[40:41], 12, v[40:41]
	v_lshl_add_u64 v[40:41], v[102:103], 0, v[40:41]
	global_load_dwordx4 v[40:43], v[40:41], off
	v_add_u32_e32 v44, 64, v30
	v_ashrrev_i32_e32 v45, 31, v44
	v_lshlrev_b64 v[44:45], 12, v[44:45]
	v_lshl_add_u64 v[44:45], v[102:103], 0, v[44:45]
	global_load_dwordx4 v[44:47], v[44:45], off
	v_add_u32_e32 v48, s79, v236
	v_ashrrev_i32_e32 v49, 31, v48
	v_lshlrev_b64 v[48:49], 12, v[48:49]
	v_lshl_add_u64 v[48:49], v[102:103], 0, v[48:49]
	global_load_dwordx4 v[48:51], v[48:49], off
	v_add_u32_e32 v52, 0x60, v30
	v_ashrrev_i32_e32 v53, 31, v52
	v_lshlrev_b64 v[52:53], 12, v[52:53]
	v_lshl_add_u64 v[52:53], v[102:103], 0, v[52:53]
	global_load_dwordx4 v[52:55], v[52:53], off
	v_add_u32_e32 v60, s79, v234
	v_ashrrev_i32_e32 v61, 31, v60
	v_lshlrev_b64 v[60:61], 12, v[60:61]
	v_lshl_add_u64 v[60:61], v[102:103], 0, v[60:61]
	global_load_dwordx4 v[60:63], v[60:61], off
	s_andn2_b64 vcc, exec, s[84:85]
	v_mov_b32_e32 v78, 0
	s_waitcnt vmcnt(7)
	ds_write_b128 v213, v[26:29]
	s_waitcnt vmcnt(6)
	ds_write_b128 v214, v[32:35]
	s_waitcnt vmcnt(5)
	ds_write_b128 v213, v[36:39] offset:16896
	s_waitcnt vmcnt(4)
	ds_write_b128 v215, v[40:43]
	s_waitcnt vmcnt(3)
	ds_write_b128 v213, v[44:47] offset:33792
	s_waitcnt vmcnt(2)
	ds_write_b128 v216, v[48:51]
	s_waitcnt vmcnt(1)
	ds_write_b128 v213, v[52:55] offset:50688
	s_waitcnt vmcnt(0)
	ds_write_b128 v217, v[60:63]
	v_mov_b32_e32 v76, v224
	v_mov_b32_e32 v77, v225
	v_mov_b32_e32 v74, v218
	v_mov_b32_e32 v75, v228
	v_add_u32_e32 v26, s79, v233
	v_ashrrev_i32_e32 v27, 31, v26
	v_lshlrev_b64 v[26:27], 12, v[26:27]
	v_lshl_add_u64 v[26:27], v[104:105], 0, v[26:27]
	global_load_dwordx4 v[54:57], v[26:27], off
	global_load_dwordx4 v[50:53], v[26:27], off offset:64
	global_load_dwordx4 v[46:49], v[26:27], off offset:128
	global_load_dwordx4 v[42:45], v[26:27], off offset:192
	global_load_dwordx4 v[38:41], v[26:27], off offset:256
	global_load_dwordx4 v[34:37], v[26:27], off offset:320
	global_load_dwordx4 v[30:33], v[26:27], off offset:384
	s_nop 0
	global_load_dwordx4 v[26:29], v[26:27], off offset:448
	s_nop 0
	s_nop 0
	global_load_dwordx4 v[58:61], v[100:101], off offset:48
	global_load_dwordx4 v[62:65], v[100:101], off offset:32
	global_load_dwordx4 v[70:73], v[100:101], off offset:16
	global_load_dwordx4 v[66:69], v[100:101], off
	s_nop 0
	v_add_u32_e32 v88, s79, v232
	v_add_u32_e32 v88, 0x80, v88
	v_ashrrev_i32_e32 v89, 31, v88
	v_lshlrev_b64 v[88:89], 12, v[88:89]
	v_lshl_add_u64 v[88:89], v[106:107], 0, v[88:89]
	global_load_dwordx2 v[224:225], v[88:89], off
	v_add_u32_e32 v88, s79, v231
	v_add_u32_e32 v88, 0x80, v88
	v_ashrrev_i32_e32 v89, 31, v88
	v_lshlrev_b64 v[88:89], 12, v[88:89]
	v_lshl_add_u64 v[88:89], v[106:107], 0, v[88:89]
	global_load_dword v218, v[88:89], off
	global_load_dword v228, v[88:89], off offset:4
	s_cbranch_vccnz .LBB0_427
	v_mov_b32_e32 v78, s33
	ds_read_b32 v80, v78
	s_waitcnt lgkmcnt(0)
	ds_bpermute_b32 v81, v227, v83
	v_max_f32_e32 v88, v87, v87
	v_max_f32_e32 v78, v80, v80
	v_max_f32_e32 v79, v86, v78
	v_max_f32_e32 v99, v88, v78
	v_sub_f32_e32 v88, v86, v79
	v_sub_f32_e32 v89, v87, v99
	v_mul_f32_e32 v88, 0x3fb8aa3b, v88
	v_mul_f32_e32 v89, 0x3fb8aa3b, v89
	v_exp_f32_e32 v88, v88
	v_exp_f32_e32 v89, v89
	ds_write_b64 v113, v[88:89]
	ds_write_b64 v114, v[86:87]
	ds_write_b64 v115, v[84:85]
	v_sub_f32_e32 v86, v80, v79
	v_add_f32_e32 v79, v82, v79
	ds_bpermute_b32 v78, v227, v99
	v_mul_f32_e32 v79, 0xbfb8aa3b, v79
	v_exp_f32_e32 v82, v79
	v_add_f32_e32 v79, v83, v99
	v_mul_f32_e32 v79, 0xbfb8aa3b, v79
	v_exp_f32_e32 v83, v79
	s_waitcnt lgkmcnt(0)
	v_sub_f32_e32 v79, v84, v78
	v_mul_f32_e32 v79, 0x3fb8aa3b, v79
	v_sub_f32_e32 v87, v80, v99
	ds_write_b64 v117, v[82:83]
	v_exp_f32_e32 v82, v79
	v_sub_f32_e32 v79, v85, v78
	v_mul_f32_e32 v86, 0x3fb8aa3b, v86
	v_mul_f32_e32 v87, 0x3fb8aa3b, v87
	v_mul_f32_e32 v79, 0x3fb8aa3b, v79
	v_exp_f32_e32 v86, v86
	v_exp_f32_e32 v87, v87
	v_exp_f32_e32 v83, v79
	ds_write_b64 v116, v[86:87]
	ds_write_b64 v118, v[82:83]
	s_and_saveexec_b64 s[52:53], s[4:5]
	s_cbranch_execz .LBB0_426
	v_sub_f32_e32 v79, v80, v78
	v_mul_f32_e32 v79, 0x3fb8aa3b, v79
	v_exp_f32_e32 v79, v79
	v_mov_b32_e32 v80, s91
	ds_write_b32 v80, v79

; __device__ __forceinline__ u16 f2bf(float f) { return (u16)(pk2(f, 0.f) & 0xffffu); }
; __device__ __forceinline__ float bflo(unsigned w) { return __uint_as_float(w << 16); }
; __device__ __forceinline__ float bfhi(unsigned w) { return __uint_as_float(w & 0xffff0000u); }
; __device__ void mlstm2_phase(const Params& p, unsigned char* smem) {
;     ...
;             for (int i = 0; i < 2; ++i) { const int t = (tid + 512 * i) >> 3; const u32x2 raw = *(const u32x2*)(XM + (size_t)(row0 + t) * 2048 + vc);
;                 const float x0 = bflo(raw.x), x1 = bfhi(raw.x), x2 = bflo(raw.y), x3 = bfhi(raw.y);
; #pragma unroll
;                 for (int jj = 0; jj < 4; ++jj) vv[i][jj] = x0 * wvp[jj] + x1 * wvp[4 + jj] + x2 * wvp[8 + jj] + x3 * wvp[12 + jj]; }
;     ...
;             __syncthreads();
;             if (tid == 0) gS[1] = m_new;
; #pragma unroll
;             for (int i = 0; i < 2; ++i) { const int t = (tid + 512 * i) >> 3; const float w = gW[t];
; #pragma unroll
;                 for (int jj = 0; jj < 4; ++jj) { const int dv = 4 * (tid & 7) + jj; Vt[dv * 136 + t] = f2bf(vv[i][jj]); Vwt[dv * 136 + t] = f2bf(vv[i][jj] * w); } }
;             if (tid < 128) Vwt[32 * 136 + tid] = f2bf(gW[tid]);
.LBB0_427:
	s_waitcnt lgkmcnt(0)
	s_barrier
	s_and_saveexec_b64 s[52:53], s[2:3]
	v_mov_b32_e32 v79, s33
	ds_write_b32 v79, v78
	s_or_b64 exec, exec, s[52:53]
	s_waitcnt vmcnt(7)
	v_lshlrev_b32_e32 v78, 16, v76
	v_and_b32_e32 v76, 0xffff0000, v76
	s_waitcnt vmcnt(4)
	v_mul_f32_e32 v80, v70, v76
	v_mul_f32_e32 v81, v71, v76
	v_mul_f32_e32 v82, v72, v76
	v_mul_f32_e32 v76, v73, v76
	v_lshlrev_b32_e32 v79, 16, v77
	s_waitcnt vmcnt(3)
	v_fmac_f32_e32 v80, v66, v78
	v_fmac_f32_e32 v81, v67, v78
	v_fmac_f32_e32 v82, v68, v78
	v_fmac_f32_e32 v76, v69, v78
	v_and_b32_e32 v77, 0xffff0000, v77
	v_fmac_f32_e32 v80, v62, v79
	v_fmac_f32_e32 v81, v63, v79
	v_fmac_f32_e32 v82, v64, v79
	v_fmac_f32_e32 v76, v65, v79
	v_fmac_f32_e32 v80, v58, v77
	v_fmac_f32_e32 v81, v59, v77
	v_fmac_f32_e32 v82, v60, v77
	v_fmac_f32_e32 v76, v61, v77
	s_waitcnt vmcnt(3)
	v_lshlrev_b32_e32 v77, 16, v74
	v_and_b32_e32 v74, 0xffff0000, v74
	v_mul_f32_e32 v70, v70, v74
	v_lshlrev_b32_e32 v78, 16, v75
	v_fmac_f32_e32 v70, v66, v77
	v_fmac_f32_e32 v70, v62, v78
	ds_read_b32 v62, v132
	v_and_b32_e32 v75, 0xffff0000, v75
	v_fmac_f32_e32 v70, v58, v75
	v_mul_f32_e32 v58, v71, v74
	v_fmac_f32_e32 v58, v67, v77
	v_fmac_f32_e32 v58, v63, v78
	v_cvt_pk_bf16_f32 v63, v80, v93
	ds_write_b16 v133, v63
	s_waitcnt lgkmcnt(1)
	v_mul_f32_e32 v63, v80, v62
	v_cvt_pk_bf16_f32 v63, v63, v93
	ds_write_b16 v134, v63
	v_cvt_pk_bf16_f32 v63, v81, v93
	ds_write_b16 v135, v63
	v_mul_f32_e32 v63, v81, v62
	v_cvt_pk_bf16_f32 v63, v63, v93
	ds_write_b16 v136, v63
	v_cvt_pk_bf16_f32 v63, v82, v93
	ds_write_b16 v137, v63
	v_mul_f32_e32 v63, v82, v62
	v_fmac_f32_e32 v58, v59, v75
	v_mul_f32_e32 v59, v72, v74
	v_cvt_pk_bf16_f32 v63, v63, v93
	v_fmac_f32_e32 v59, v68, v77
	ds_write_b16 v138, v63
	v_cvt_pk_bf16_f32 v63, v76, v93
	v_mul_f32_e32 v62, v76, v62
	v_fmac_f32_e32 v59, v64, v78
	ds_write_b16 v139, v63
	v_cvt_pk_bf16_f32 v62, v62, v93
	ds_read_b32 v63, v141
	v_fmac_f32_e32 v59, v60, v75
	v_mul_f32_e32 v60, v73, v74
	v_fmac_f32_e32 v60, v69, v77
	v_fmac_f32_e32 v60, v65, v78
	v_fmac_f32_e32 v60, v61, v75
	ds_write_b16 v140, v62
	v_cvt_pk_bf16_f32 v61, v70, v93
	ds_write_b16 v142, v61
	s_waitcnt lgkmcnt(2)
	v_mul_f32_e32 v61, v70, v63
	v_cvt_pk_bf16_f32 v61, v61, v93
	ds_write_b16 v143, v61
	v_cvt_pk_bf16_f32 v61, v58, v93
	v_mul_f32_e32 v58, v58, v63
	ds_write_b16 v144, v61
	v_cvt_pk_bf16_f32 v58, v58, v93
	ds_write_b16 v145, v58
	v_cvt_pk_bf16_f32 v58, v59, v93
	ds_write_b16 v146, v58
	v_mul_f32_e32 v58, v59, v63
	v_cvt_pk_bf16_f32 v58, v58, v93
	ds_write_b16 v147, v58
	v_cvt_pk_bf16_f32 v58, v60, v93
	ds_write_b16 v148, v58
	v_mul_f32_e32 v58, v60, v63
	v_cvt_pk_bf16_f32 v58, v58, v93
	ds_write_b16 v149, v58
	s_and_saveexec_b64 s[52:53], s[6:7]
	s_cbranch_execz .LBB0_431
	ds_read_b32 v58, v120
	s_waitcnt lgkmcnt(0)
	v_cvt_pk_bf16_f32 v58, v58, v93
	ds_write_b16 v119, v58 offset:8704
